# v60 plus a guard: XCD-local barriers are enabled only when gridDim.x == 256 (the tile-ownership analysis assumes it) and every blockIdx%8 group sits on one XCC
# baseline (speedup 1.0000x reference)
.LBB0_79:
	v_mov_b32_e32 v15, 0
	s_mov_b32 s1, 0xcd99adac
	s_lshr_b32 s1, s1, s21
	s_bitcmp1_b32 s1, 0
	s_cbranch_scc0 .Larr_done
	v_mov_b32_e32 v12, 0x23808
	ds_read_b32 v13, v12
	s_waitcnt lgkmcnt(0)
	v_readfirstlane_b32 s1, v13
	s_cmp_lg_u32 s1, 0
	s_cbranch_scc1 .Larr_have_flag
	v_mov_b32_e32 v13, 2
	v_readlane_b32 s10, v253, 10
	s_nop 0
	s_cmp_eq_u32 s10, 0
	s_cbranch_scc1 .Larr_store_flag
	v_mov_b32_e32 v14, 0x3600
	global_load_dwordx4 v[4:7], v14, s[24:25] sc1
	global_load_dwordx4 v[8:11], v14, s[24:25] offset:16 sc1
	s_waitcnt vmcnt(0)
	v_add_u32_e32 v13, -1, v4
	v_and_b32_e32 v16, v13, v4
	v_min_u32_e32 v14, v4, v5
	v_add_u32_e32 v13, -1, v5
	v_and_b32_e32 v13, v13, v5
	v_or_b32_e32 v16, v16, v13
	v_add_u32_e32 v13, -1, v6
	v_and_b32_e32 v13, v13, v6
	v_or_b32_e32 v16, v16, v13
	v_min_u32_e32 v14, v14, v6
	v_add_u32_e32 v13, -1, v7
	v_and_b32_e32 v13, v13, v7
	v_or_b32_e32 v16, v16, v13
	v_min_u32_e32 v14, v14, v7
	v_add_u32_e32 v13, -1, v8
	v_and_b32_e32 v13, v13, v8
	v_or_b32_e32 v16, v16, v13
	v_min_u32_e32 v14, v14, v8
	v_add_u32_e32 v13, -1, v9
	v_and_b32_e32 v13, v13, v9
	v_or_b32_e32 v16, v16, v13
	v_min_u32_e32 v14, v14, v9
	v_add_u32_e32 v13, -1, v10
	v_and_b32_e32 v13, v13, v10
	v_or_b32_e32 v16, v16, v13
	v_min_u32_e32 v14, v14, v10
	v_add_u32_e32 v13, -1, v11
	v_and_b32_e32 v13, v13, v11
	v_or_b32_e32 v16, v16, v13
	v_min_u32_e32 v14, v14, v11
	v_cmp_eq_u32_e32 vcc, 0, v16
	v_cmp_ne_u32_e64 s[10:11], 0, v14
	s_and_b64 s[10:11], s[10:11], vcc
	v_cndmask_b32_e64 v13, 2, 1, s[10:11]
.Larr_store_flag:
	ds_write_b32 v12, v13
	s_nop 1
	v_readfirstlane_b32 s1, v13
